# k29 + grid-barrier poll keeps two staggered loads of the TOP counter in flight
# speedup vs baseline: 1.0048x; 1.0002x over previous
.Lxb_spin:
	global_load_dword v0, v177, s[4:5] sc1
	s_sleep 12
.Lxb_spin2:
	global_load_dword v4, v177, s[4:5] sc1
	s_waitcnt vmcnt(1)
	v_sub_u32_e32 v0, v0, v1
	v_cmp_le_i32_e32 vcc, 0, v0
	s_cbranch_vccnz .Lxb_done
	global_load_dword v0, v177, s[4:5] sc1
	s_waitcnt vmcnt(1)
	v_sub_u32_e32 v4, v4, v1
	v_cmp_le_i32_e32 vcc, 0, v4
	s_cbranch_vccnz .Lxb_done
	s_add_i32 s16, s16, 1
	s_and_b32 s12, s16, 0xff
	s_cmp_lg_u32 s12, 0
	s_cbranch_scc1 .Lxb_spin2
	s_waitcnt vmcnt(0)
	global_load_dword v5, v177, s[82:83] sc1
	s_waitcnt vmcnt(0)
	v_cmp_ne_u32_e32 vcc, 0, v5
	s_cbranch_vccnz .Lxb_done
	s_cmp_lt_u32 s16, 0x400001
	s_cbranch_scc1 .Lxb_spin
	v_mov_b32_e32 v0, 1
	global_atomic_add v177, v0, s[82:83]
